# attnA: loop-invariant V fragment addresses hoisted, redundant max canonicalisation and zero-add removed (bit-identical)
# speedup vs baseline: 1.0608x; 1.0035x over previous
.LBB0_177:
	v_and_b32_e32 v0, 63, v154
	v_readlane_b32 s4, v245, 5
	v_lshlrev_b32_e32 v0, 2, v0
	v_readlane_b32 s14, v245, 15
	v_readlane_b32 s15, v245, 16
	s_nop 4
	global_load_dword v1, v0, s[14:15]
	global_load_dword v2, v0, s[14:15] offset:256
	global_load_dword v3, v0, s[14:15] offset:512
	global_load_dword v4, v0, s[14:15] offset:768
	v_mbcnt_lo_u32_b32 v0, -1, 0
	v_mbcnt_hi_u32_b32 v12, -1, v0
	v_and_b32_e32 v17, 64, v12
	v_xor_b32_e32 v18, 32, v12
	v_add_u32_e32 v17, 64, v17
	v_lshrrev_b32_e32 v5, 6, v154
	v_bfe_u32 v10, v154, 4, 2
	v_bfe_u32 v11, v154, 3, 3
	v_cmp_lt_i32_e32 vcc, v18, v17
	v_or_b32_e32 v13, 0x7fffffe0, v10
	v_lshl_or_b32 v16, v5, 3, v11
	v_cndmask_b32_e32 v18, v12, v18, vcc
	s_movk_i32 s20, 0x1800
	v_lshl_add_u32 v24, v5, 2, v13
	v_lshrrev_b32_e32 v25, 1, v16
	v_lshlrev_b32_e32 v158, 2, v18
	v_mul_lo_u32 v157, v24, s20
	v_xor_b32_e32 v24, v25, v154
	v_xor_b32_e32 v19, 16, v12
	v_cmp_lt_i32_e32 vcc, v19, v17
	v_xor_b32_e32 v20, 8, v12
	v_xor_b32_e32 v21, 4, v12
	v_cndmask_b32_e32 v19, v12, v19, vcc
	v_lshlrev_b32_e32 v19, 2, v19
	v_cmp_lt_i32_e32 vcc, v20, v17
	v_xor_b32_e32 v22, 2, v12
	v_xor_b32_e32 v23, 1, v12
	v_cndmask_b32_e32 v20, v12, v20, vcc
	v_cmp_lt_i32_e32 vcc, v21, v17
	v_readlane_b32 s8, v245, 9
	s_mov_b32 s8, 0x3fb8aa3b
	v_readlane_b32 s12, v245, 13
	s_mov_b32 s12, 0xc2ce8ed0
	v_readlane_b32 s13, v245, 14
	s_mov_b32 s13, 0x42b17218
	v_mov_b32_e32 v8, 0x7f800000
	v_add_u32_e32 v15, 4, v5
	v_readlane_b32 s10, v245, 11
	v_readlane_b32 s11, v245, 12
	s_not_b32 s4, s2
	s_ashr_i32 s3, s2, 31
	v_lshlrev_b32_e32 v14, 2, v10
	v_and_b32_e32 v6, 31, v154
	v_bfe_u32 v7, v154, 5, 1
	s_add_i32 s21, s33, s4
	s_lshl_b64 s[10:11], s[2:3], 16
	v_bitop3_b32 v14, v14, v154, 12 bitop3:0x78
	v_bfe_u32 v9, v154, 2, 2
	v_mul_u32_u24_e32 v16, 0xc00, v16
	v_lshl_add_u32 v13, v15, 2, v13
	v_and_or_b32 v14, v154, 3, v14
	v_lshl_or_b32 v172, v5, 5, v6
	s_add_u32 s10, s38, s10
	s_movk_i32 s3, 0x6000
	v_readlane_b32 s5, v245, 6
	v_readlane_b32 s6, v245, 7
	v_mov_b32_e32 v113, 0
	v_lshlrev_b32_e32 v156, 10, v5
	v_lshlrev_b32_e32 v14, 4, v14
	v_mul_lo_u32 v166, v13, s20
	v_lshlrev_b32_e32 v168, 6, v9
	s_addc_u32 s11, s39, s11
	v_lshlrev_b32_e32 v112, 8, v154
	v_readlane_b32 s7, v245, 8
	v_readlane_b32 s9, v245, 10
	v_readlane_b32 s16, v245, 17
	v_readlane_b32 s17, v245, 18
	s_movk_i32 s5, 0x200
	s_movk_i32 s6, 0x100
	v_lshlrev_b32_e32 v0, 3, v7
	v_lshl_add_u64 v[114:115], s[10:11], 0, v[112:113]
	v_lshlrev_b32_e32 v112, 4, v7
	s_mov_b32 s9, 0
	v_lshrrev_b32_e32 v155, 7, v154
	v_cmp_gt_u32_e64 s[4:5], s5, v154
	v_cmp_gt_u32_e64 s[6:7], s6, v154
	v_add_u32_e32 v159, 0x30000, v157
	s_waitcnt vmcnt(2)
	v_mul_f32_e32 v18, v1, v2
	ds_bpermute_b32 v18, v158, v18
	s_waitcnt vmcnt(0)
	v_mul_f32_e32 v25, v3, v4
	ds_bpermute_b32 v25, v158, v25
	v_add_u32_e32 v160, 0x48000, v157
	v_add_u32_e32 v161, 0x60000, v157
	s_waitcnt lgkmcnt(1)
	v_fmac_f32_e32 v18, v1, v2
	ds_bpermute_b32 v1, v19, v18
	s_waitcnt lgkmcnt(1)
	v_fmac_f32_e32 v25, v3, v4
	ds_bpermute_b32 v2, v19, v25
	v_lshlrev_b32_e32 v4, 2, v20
	v_cndmask_b32_e32 v3, v12, v21, vcc
	s_waitcnt lgkmcnt(1)
	v_add_f32_e32 v1, v18, v1
	ds_bpermute_b32 v18, v4, v1
	s_waitcnt lgkmcnt(1)
	v_add_f32_e32 v2, v25, v2
	ds_bpermute_b32 v4, v4, v2
	v_lshlrev_b32_e32 v3, 2, v3
	v_cmp_lt_i32_e32 vcc, v22, v17
	s_waitcnt lgkmcnt(1)
	v_add_f32_e32 v1, v1, v18
	v_add_u32_e32 v162, 0x78000, v157
	s_waitcnt lgkmcnt(0)
	v_add_f32_e32 v2, v2, v4
	ds_bpermute_b32 v4, v3, v1
	ds_bpermute_b32 v3, v3, v2
	v_cndmask_b32_e32 v19, v12, v22, vcc
	v_cmp_lt_i32_e32 vcc, v23, v17
	v_lshlrev_b32_e32 v17, 2, v19
	s_waitcnt lgkmcnt(1)
	v_add_f32_e32 v1, v1, v4
	s_waitcnt lgkmcnt(0)
	v_add_f32_e32 v2, v2, v3
	ds_bpermute_b32 v3, v17, v1
	ds_bpermute_b32 v4, v17, v2
	v_cndmask_b32_e32 v12, v12, v23, vcc
	v_lshlrev_b32_e32 v12, 2, v12
	v_or_b32_e32 v163, 0x1000, v14
	s_waitcnt lgkmcnt(1)
	v_add_f32_e32 v1, v1, v3
	s_waitcnt lgkmcnt(0)
	v_add_f32_e32 v2, v2, v4
	ds_bpermute_b32 v3, v12, v1
	ds_bpermute_b32 v4, v12, v2
	v_lshlrev_b32_e32 v12, 3, v24
	v_and_or_b32 v164, v12, 56, v16
	v_xor_b32_e32 v169, 64, v168
	s_waitcnt lgkmcnt(1)
	v_add_f32_e32 v1, v1, v3
	s_waitcnt lgkmcnt(0)
	v_add_f32_e32 v2, v2, v4
	v_mul_f32_e32 v3, 0x3fb8aa3b, v1
	v_mul_f32_e32 v4, 0x3fb8aa3b, v2
	v_fma_f32 v17, v1, s8, -v3
	v_rndne_f32_e32 v18, v3
	v_fma_f32 v19, v2, s8, -v4
	v_rndne_f32_e32 v20, v4
	v_fmac_f32_e32 v17, 0x32a5705f, v1
	v_sub_f32_e32 v3, v3, v18
	v_fmac_f32_e32 v19, 0x32a5705f, v2
	v_sub_f32_e32 v4, v4, v20
	v_add_f32_e32 v3, v3, v17
	v_cvt_i32_f32_e32 v18, v18
	v_add_f32_e32 v4, v4, v19
	v_exp_f32_e32 v3, v3
	v_cvt_i32_f32_e32 v20, v20
	v_exp_f32_e32 v4, v4
	v_cmp_ngt_f32_e32 vcc, s12, v1
	v_ldexp_f32 v3, v3, v18
	v_xor_b32_e32 v170, 0x80, v168
	v_ldexp_f32 v4, v4, v20
	v_cndmask_b32_e32 v3, 0, v3, vcc
	v_cmp_ngt_f32_e32 vcc, s12, v2
	v_xor_b32_e32 v171, 0xc0, v168
	v_lshl_add_u64 v[116:117], s[16:17], 0, v[112:113]
	v_cndmask_b32_e32 v4, 0, v4, vcc
	v_cmp_nlt_f32_e32 vcc, s13, v1
	v_lshlrev_b32_e32 v118, 1, v0
	v_add_u32_e32 v178, 0x1000, v156
	v_cndmask_b32_e32 v1, v8, v3, vcc
	v_cmp_nlt_f32_e32 vcc, s13, v2
	v_lshrrev_b32_e32 v3, 1, v154
	v_bitop3_b32 v3, v7, v3, 7 bitop3:0x78
	v_cndmask_b32_e32 v2, v8, v4, vcc
	v_sub_f32_e32 v1, v1, v2
	v_add_f32_e32 v165, 0x3e4ccccd, v1
	v_lshl_or_b32 v1, v15, 3, v11
	v_lshrrev_b32_e32 v2, 1, v1
	v_xor_b32_e32 v2, v2, v154
	v_mul_u32_u24_e32 v1, 0xc00, v1
	v_lshlrev_b32_e32 v2, 3, v2
	v_and_or_b32 v167, v2, 56, v1
	v_lshlrev_b32_e32 v1, 7, v6
	v_bfe_u32 v4, v154, 1, 3
	v_lshlrev_b32_e32 v2, 2, v7
	v_mul_u32_u24_e32 v6, 0x1800, v10
	v_lshlrev_b32_e32 v8, 1, v154
	v_lshlrev_b32_e32 v11, 3, v154
	v_bitop3_b32 v12, v7, v4, 2 bitop3:0x36
	v_bitop3_b32 v13, v7, v4, 4 bitop3:0x36
	v_bitop3_b32 v4, v7, v4, 6 bitop3:0x36
	v_or_b32_e32 v9, v2, v9
	v_mad_u32_u24 v5, v5, s3, v6
	v_and_b32_e32 v8, 32, v8
	v_and_b32_e32 v11, 24, v11
	v_lshlrev_b32_e32 v3, 4, v3
	v_lshlrev_b32_e32 v12, 4, v12
	v_lshlrev_b32_e32 v13, 4, v13
	v_lshlrev_b32_e32 v4, 4, v4
	v_lshlrev_b32_e32 v9, 8, v9
	v_or_b32_e32 v5, v5, v14
	v_or3_b32 v173, v8, v11, v9
	v_add_u32_e32 v174, 0x1000, v5
	v_add_u32_e32 v175, 0x19000, v5
	v_add_u32_e32 v176, 0x31000, v5
	v_add_u32_e32 v177, 0x49000, v5
	v_add_u32_e32 v179, 0x2000, v156
	v_add_u32_e32 v180, 0x3000, v156
	v_or_b32_e32 v181, 0x4000, v156
	v_add_u32_e32 v182, 0x5000, v156
	s_mov_b64 s[10:11], 0x60000
	v_add_u32_e32 v183, 0x6000, v156
	v_add_u32_e32 v184, 0x7000, v156
	v_or_b32_e32 v185, 0x8000, v156
	v_add_u32_e32 v186, 0x9000, v156
	v_add_u32_e32 v187, 0xa000, v156
	v_add_u32_e32 v188, 0xb000, v156
	v_add_u32_e32 v189, v1, v3
	v_add_u32_e32 v190, v1, v12
	v_add_u32_e32 v191, v1, v13
	v_add_u32_e32 v192, v1, v4
	s_mov_b32 s3, 0x3e38aa3b
	s_mov_b64 s[12:13], 0xc0000
	v_lshlrev_b32_e32 v120, 1, v2
	v_mov_b32_e32 v193, 0x3727c5ac
	s_mov_b32 s22, 0x800000
	s_mov_b32 s8, 0
	s_mov_b32 s23, 0
	v_readlane_b32 s18, v245, 19
	v_readlane_b32 s19, v245, 20
	s_nop 0
	v_readfirstlane_b32 s72, v183
	v_readfirstlane_b32 s73, v184
	v_readfirstlane_b32 s74, v185
	v_readfirstlane_b32 s75, v186
	v_readfirstlane_b32 s76, v187
	v_readfirstlane_b32 s77, v188
	v_readfirstlane_b32 s78, v156
	v_readfirstlane_b32 s79, v178
	v_readfirstlane_b32 s80, v179
	v_readfirstlane_b32 s81, v180
	v_readfirstlane_b32 s82, v181
	v_readfirstlane_b32 s83, v182
	v_add_u32_e32 v236, v173, v168
	v_add_u32_e32 v237, v173, v169
	v_add_u32_e32 v238, v173, v170
	v_add_u32_e32 v239, v173, v171
	s_branch .LBB0_180

.LBB0_182:
	v_fma_f32 v80, v80, s3, -v197
	v_exp_f32_e32 v80, v80
	v_fma_f32 v81, v81, s3, -v197
	v_fma_f32 v82, v82, s3, -v197
	v_exp_f32_e32 v81, v81
	v_exp_f32_e32 v82, v82
	v_fma_f32 v83, v83, s3, -v197
	v_exp_f32_e32 v83, v83
	v_fma_f32 v84, v84, s3, -v197
	v_exp_f32_e32 v143, v84
	v_fma_f32 v85, v85, s3, -v197
	v_add_f32_e32 v84, v81, v80
	v_exp_f32_e32 v142, v85
	v_fma_f32 v85, v86, s3, -v197
	v_add_f32_e32 v84, v82, v84
	v_exp_f32_e32 v144, v85
	v_fma_f32 v85, v87, s3, -v197
	v_add_f32_e32 v84, v83, v84
	v_exp_f32_e32 v145, v85
	v_fma_f32 v85, v88, s3, -v197
	v_add_f32_e32 v84, v143, v84
	v_exp_f32_e32 v198, v85
	v_add_f32_e32 v84, v142, v84
	v_add_f32_e32 v84, v144, v84
	v_add_f32_e32 v84, v145, v84
	v_add_f32_e32 v88, v198, v84
	v_fma_f32 v84, v89, s3, -v197
	v_exp_f32_e32 v199, v84
	v_fma_f32 v84, v90, s3, -v197
	v_exp_f32_e32 v200, v84
	ds_read_b64_tr_b16 v[84:85], v236 offset:32768
	ds_read_b64_tr_b16 v[86:87], v236 offset:34816
	v_cvt_pk_bf16_f32 v80, v80, v81
	v_cvt_pk_bf16_f32 v81, v82, v83
	v_cvt_pk_bf16_f32 v82, v143, v142
	v_cvt_pk_bf16_f32 v83, v144, v145
	ds_read_b64_tr_b16 v[142:143], v237 offset:32768
	ds_read_b64_tr_b16 v[144:145], v237 offset:34816
	ds_read_b64_tr_b16 v[146:147], v236 offset:36864
	ds_read_b64_tr_b16 v[148:149], v236 offset:38912
	s_waitcnt lgkmcnt(4)
	v_mfma_f32_32x32x16_bf16 v[48:63], v[84:87], v[80:83], v[48:63]
	v_add_f32_e32 v84, v199, v88
	v_add_f32_e32 v203, v200, v84
	ds_read_b64_tr_b16 v[84:85], v238 offset:32768
	ds_read_b64_tr_b16 v[86:87], v238 offset:34816
	ds_read_b64_tr_b16 v[150:151], v237 offset:36864
	ds_read_b64_tr_b16 v[152:153], v237 offset:38912
	v_fma_f32 v88, v91, s3, -v197
	v_exp_f32_e32 v205, v88
	s_waitcnt lgkmcnt(6)
	v_mfma_f32_32x32x16_bf16 v[32:47], v[142:145], v[80:83], v[32:47]
	ds_read_b64_tr_b16 v[88:89], v239 offset:32768
	ds_read_b64_tr_b16 v[90:91], v239 offset:34816
	ds_read_b64_tr_b16 v[142:143], v238 offset:36864
	ds_read_b64_tr_b16 v[144:145], v238 offset:38912
	v_fma_f32 v94, v94, s3, -v197
	v_exp_f32_e32 v94, v94
	v_fma_f32 v64, v64, s3, -v197
	v_fma_f32 v78, v78, s3, -v197
	s_waitcnt lgkmcnt(6)
	v_mfma_f32_32x32x16_bf16 v[16:31], v[84:87], v[80:83], v[16:31]
	v_fma_f32 v84, v92, s3, -v197
	v_exp_f32_e32 v92, v84
	v_fma_f32 v84, v93, s3, -v197
	v_exp_f32_e32 v93, v84
	ds_read_b64_tr_b16 v[84:85], v239 offset:36864
	ds_read_b64_tr_b16 v[86:87], v239 offset:38912
	s_waitcnt lgkmcnt(4)
	v_mfma_f32_32x32x16_bf16 v[0:15], v[88:91], v[80:83], v[0:15]
	v_fma_f32 v80, v95, s3, -v197
	v_exp_f32_e32 v95, v80
	v_cvt_pk_bf16_f32 v80, v198, v199
	v_cvt_pk_bf16_f32 v81, v200, v205
	v_cvt_pk_bf16_f32 v82, v92, v93
	v_cvt_pk_bf16_f32 v83, v94, v95
	s_nop 1
	v_mfma_f32_32x32x16_bf16 v[48:63], v[146:149], v[80:83], v[48:63]
	v_exp_f32_e32 v146, v64
	v_fma_f32 v64, v65, s3, -v197
	v_exp_f32_e32 v147, v64
	v_fma_f32 v64, v66, s3, -v197
	v_exp_f32_e32 v148, v64
	v_fma_f32 v64, v67, s3, -v197
	v_exp_f32_e32 v149, v64
	v_fma_f32 v64, v68, s3, -v197
	v_mfma_f32_32x32x16_bf16 v[32:47], v[150:153], v[80:83], v[32:47]
	v_exp_f32_e32 v150, v64
	v_fma_f32 v64, v69, s3, -v197
	v_exp_f32_e32 v151, v64
	v_fma_f32 v64, v70, s3, -v197
	v_exp_f32_e32 v152, v64
	v_fma_f32 v64, v71, s3, -v197
	ds_read_b64_tr_b16 v[68:69], v236 offset:40960
	ds_read_b64_tr_b16 v[70:71], v236 offset:43008
	s_waitcnt lgkmcnt(4)
	v_mfma_f32_32x32x16_bf16 v[16:31], v[142:145], v[80:83], v[16:31]
	v_exp_f32_e32 v142, v64
	v_fma_f32 v64, v72, s3, -v197
	v_exp_f32_e32 v143, v64
	v_cvt_pk_bf16_f32 v64, v146, v147
	v_cvt_pk_bf16_f32 v65, v148, v149
	v_cvt_pk_bf16_f32 v66, v150, v151
	v_cvt_pk_bf16_f32 v67, v152, v142
	s_waitcnt lgkmcnt(2)
	v_mfma_f32_32x32x16_bf16 v[0:15], v[84:87], v[80:83], v[0:15]
	ds_read_b64_tr_b16 v[80:81], v237 offset:40960
	ds_read_b64_tr_b16 v[82:83], v237 offset:43008
	ds_read_b64_tr_b16 v[84:85], v236 offset:45056
	ds_read_b64_tr_b16 v[86:87], v236 offset:47104
	v_fma_f32 v72, v74, s3, -v197
	v_exp_f32_e32 v145, v72
	v_fma_f32 v72, v75, s3, -v197
	v_exp_f32_e32 v153, v72
	s_waitcnt lgkmcnt(4)
	v_mfma_f32_32x32x16_bf16 v[48:63], v[68:71], v[64:67], v[48:63]
	v_fma_f32 v68, v73, s3, -v197
	v_exp_f32_e32 v144, v68
	ds_read_b64_tr_b16 v[68:69], v238 offset:40960
	ds_read_b64_tr_b16 v[70:71], v238 offset:43008
	ds_read_b64_tr_b16 v[88:89], v237 offset:45056
	ds_read_b64_tr_b16 v[90:91], v237 offset:47104
	s_waitcnt lgkmcnt(6)
	v_mfma_f32_32x32x16_bf16 v[32:47], v[80:83], v[64:67], v[32:47]
	ds_read_b64_tr_b16 v[72:73], v239 offset:40960
	ds_read_b64_tr_b16 v[74:75], v239 offset:43008
	ds_read_b64_tr_b16 v[80:81], v238 offset:45056
	ds_read_b64_tr_b16 v[82:83], v238 offset:47104
	s_waitcnt lgkmcnt(2)
	v_mfma_f32_32x32x16_bf16 v[0:15], v[72:75], v[64:67], v[0:15]
	v_add_f32_e32 v74, v205, v203
	v_add_f32_e32 v74, v92, v74
	v_add_f32_e32 v74, v93, v74
	v_add_f32_e32 v74, v94, v74
	v_add_f32_e32 v74, v95, v74
	v_add_f32_e32 v74, v146, v74
	v_add_f32_e32 v74, v147, v74
	v_mfma_f32_32x32x16_bf16 v[16:31], v[68:71], v[64:67], v[16:31]
	v_fma_f32 v68, v76, s3, -v197
	v_add_f32_e32 v74, v148, v74
	v_exp_f32_e32 v76, v68
	v_fma_f32 v68, v77, s3, -v197
	v_fma_f32 v64, v79, s3, -v197
	v_add_f32_e32 v74, v149, v74
	v_exp_f32_e32 v77, v68
	ds_read_b64_tr_b16 v[68:69], v239 offset:45056
	ds_read_b64_tr_b16 v[70:71], v239 offset:47104
	v_exp_f32_e32 v72, v78
	v_exp_f32_e32 v73, v64
	v_add_f32_e32 v74, v150, v74
	v_add_f32_e32 v74, v151, v74
	v_add_f32_e32 v74, v152, v74
	v_add_f32_e32 v74, v142, v74
	v_cvt_pk_bf16_f32 v64, v143, v144
	v_cvt_pk_bf16_f32 v65, v145, v153
	v_cvt_pk_bf16_f32 v66, v76, v77
	v_cvt_pk_bf16_f32 v67, v72, v73
	v_add_f32_e32 v74, v143, v74
	v_add_f32_e32 v74, v144, v74
	v_mfma_f32_32x32x16_bf16 v[48:63], v[84:87], v[64:67], v[48:63]
	v_add_f32_e32 v74, v145, v74
	v_add_f32_e32 v74, v153, v74
	v_add_f32_e32 v74, v76, v74
	v_add_f32_e32 v74, v77, v74
	v_add_f32_e32 v72, v72, v74
	v_add_f32_e32 v72, v73, v72
	v_add_f32_e32 v196, v196, v72
	v_mfma_f32_32x32x16_bf16 v[32:47], v[88:91], v[64:67], v[32:47]
	s_waitcnt lgkmcnt(2)
	v_mfma_f32_32x32x16_bf16 v[16:31], v[80:83], v[64:67], v[16:31]
	s_waitcnt lgkmcnt(0)
	v_mfma_f32_32x32x16_bf16 v[0:15], v[68:71], v[64:67], v[0:15]

.LBB0_186:
	v_cmp_le_u32_e32 vcc, s8, v119
	s_and_saveexec_b64 s[18:19], vcc
	s_cbranch_execz .LBB0_190
	ds_read_b128 v[220:223], v189
	ds_read_b128 v[68:71], v189 offset:4096
	ds_read_b128 v[224:227], v190
	ds_read_b128 v[198:201], v190 offset:4096
	ds_read_b128 v[228:231], v191
	ds_read_b128 v[202:205], v191 offset:4096
	ds_read_b128 v[232:235], v192
	ds_read_b128 v[206:209], v192 offset:4096
	s_waitcnt lgkmcnt(7)
	v_mfma_f32_32x32x16_bf16 v[80:95], v[220:223], v[96:99], 0
	s_waitcnt lgkmcnt(5)
	v_mfma_f32_32x32x16_bf16 v[80:95], v[224:227], v[100:103], v[80:95]
	s_waitcnt lgkmcnt(3)
	v_mfma_f32_32x32x16_bf16 v[80:95], v[228:231], v[104:107], v[80:95]
	s_waitcnt lgkmcnt(1)
	v_mfma_f32_32x32x16_bf16 v[80:95], v[232:235], v[108:111], v[80:95]
	s_waitcnt lgkmcnt(0)
	v_mfma_f32_32x32x16_bf16 v[64:79], v[68:71], v[96:99], 0
	v_mfma_f32_32x32x16_bf16 v[64:79], v[198:201], v[100:103], v[64:79]
	s_nop 9
	v_max_f32_e32 v198, v80, v81
	v_max3_f32 v198, v198, v82, v83
	v_max3_f32 v198, v198, v84, v85
	v_max3_f32 v198, v198, v86, v87
	v_max3_f32 v198, v198, v88, v89
	v_mfma_f32_32x32x16_bf16 v[64:79], v[202:205], v[104:107], v[64:79]
	v_max3_f32 v198, v198, v90, v91
	v_max3_f32 v198, v198, v92, v93
	v_max3_f32 v198, v198, v94, v95
	v_mfma_f32_32x32x16_bf16 v[64:79], v[206:209], v[108:111], v[64:79]
	s_nop 11
	v_max3_f32 v198, v198, v64, v65
	v_max3_f32 v198, v198, v66, v67
	v_max3_f32 v198, v198, v68, v69
	v_max3_f32 v198, v198, v70, v71
	v_max3_f32 v198, v198, v72, v73
	v_max3_f32 v198, v198, v74, v75
	v_max3_f32 v198, v198, v76, v77
	v_max3_f32 v198, v198, v78, v79
	v_mov_b32_e32 v199, v198
	s_nop 1
	v_permlane32_swap_b32_e32 v198, v199
	v_max_f32_e32 v198, v198, v199
	v_mul_f32_e32 v198, 0x3e38aa3b, v198
	v_add_f32_e32 v199, 0x41000000, v197
	v_cmp_gt_f32_e32 vcc, v198, v199
	s_cbranch_vccz .LBB0_189
	s_nop 0
	v_cndmask_b32_e32 v199, v197, v198, vcc
	v_sub_f32_e32 v197, v197, v199
	v_exp_f32_e32 v198, v197
	v_mov_b32_e32 v197, v199
	v_pk_mul_f32 v[62:63], v[62:63], v[198:199] op_sel_hi:[1,0]
	v_pk_mul_f32 v[60:61], v[60:61], v[198:199] op_sel_hi:[1,0]
	v_pk_mul_f32 v[58:59], v[58:59], v[198:199] op_sel_hi:[1,0]
	v_pk_mul_f32 v[56:57], v[56:57], v[198:199] op_sel_hi:[1,0]
	v_pk_mul_f32 v[54:55], v[54:55], v[198:199] op_sel_hi:[1,0]
	v_pk_mul_f32 v[52:53], v[52:53], v[198:199] op_sel_hi:[1,0]
	v_pk_mul_f32 v[50:51], v[50:51], v[198:199] op_sel_hi:[1,0]
	v_pk_mul_f32 v[48:49], v[48:49], v[198:199] op_sel_hi:[1,0]
	v_pk_mul_f32 v[46:47], v[46:47], v[198:199] op_sel_hi:[1,0]
	v_pk_mul_f32 v[44:45], v[44:45], v[198:199] op_sel_hi:[1,0]
	v_pk_mul_f32 v[42:43], v[42:43], v[198:199] op_sel_hi:[1,0]
	v_pk_mul_f32 v[40:41], v[40:41], v[198:199] op_sel_hi:[1,0]
	v_pk_mul_f32 v[38:39], v[38:39], v[198:199] op_sel_hi:[1,0]
	v_pk_mul_f32 v[36:37], v[36:37], v[198:199] op_sel_hi:[1,0]
	v_pk_mul_f32 v[34:35], v[34:35], v[198:199] op_sel_hi:[1,0]
	v_pk_mul_f32 v[32:33], v[32:33], v[198:199] op_sel_hi:[1,0]
	v_pk_mul_f32 v[30:31], v[30:31], v[198:199] op_sel_hi:[1,0]
	v_pk_mul_f32 v[28:29], v[28:29], v[198:199] op_sel_hi:[1,0]
	v_pk_mul_f32 v[26:27], v[26:27], v[198:199] op_sel_hi:[1,0]
	v_pk_mul_f32 v[24:25], v[24:25], v[198:199] op_sel_hi:[1,0]
	v_pk_mul_f32 v[22:23], v[22:23], v[198:199] op_sel_hi:[1,0]
	v_pk_mul_f32 v[20:21], v[20:21], v[198:199] op_sel_hi:[1,0]
	v_pk_mul_f32 v[18:19], v[18:19], v[198:199] op_sel_hi:[1,0]
	v_pk_mul_f32 v[16:17], v[16:17], v[198:199] op_sel_hi:[1,0]
	v_pk_mul_f32 v[14:15], v[14:15], v[198:199] op_sel_hi:[1,0]
	v_pk_mul_f32 v[12:13], v[12:13], v[198:199] op_sel_hi:[1,0]
	v_pk_mul_f32 v[10:11], v[10:11], v[198:199] op_sel_hi:[1,0]
	v_pk_mul_f32 v[8:9], v[8:9], v[198:199] op_sel_hi:[1,0]
	v_pk_mul_f32 v[6:7], v[6:7], v[198:199] op_sel_hi:[1,0]
	v_pk_mul_f32 v[4:5], v[4:5], v[198:199] op_sel_hi:[1,0]
	v_pk_mul_f32 v[2:3], v[2:3], v[198:199] op_sel_hi:[1,0]
	v_pk_mul_f32 v[0:1], v[0:1], v[198:199] op_sel_hi:[1,0]
	v_mul_f32_e32 v196, v196, v198
.LBB0_189:
	v_fma_f32 v80, v80, s3, -v197
	v_exp_f32_e32 v80, v80
	v_fma_f32 v81, v81, s3, -v197
	v_fma_f32 v82, v82, s3, -v197
	v_exp_f32_e32 v81, v81
	v_exp_f32_e32 v82, v82
	v_fma_f32 v83, v83, s3, -v197
	v_exp_f32_e32 v83, v83
	v_fma_f32 v84, v84, s3, -v197
	v_exp_f32_e32 v199, v84
	v_fma_f32 v85, v85, s3, -v197
	v_add_f32_e32 v84, v81, v80
	v_exp_f32_e32 v198, v85
	v_fma_f32 v85, v86, s3, -v197
	v_add_f32_e32 v84, v82, v84
	v_exp_f32_e32 v200, v85
	v_fma_f32 v85, v87, s3, -v197
	v_add_f32_e32 v84, v83, v84
	v_exp_f32_e32 v201, v85
	v_fma_f32 v85, v88, s3, -v197
	v_add_f32_e32 v84, v199, v84
	v_exp_f32_e32 v210, v85
	v_add_f32_e32 v84, v198, v84
	v_add_f32_e32 v84, v200, v84
	v_add_f32_e32 v84, v201, v84
	v_add_f32_e32 v88, v210, v84
	v_fma_f32 v84, v89, s3, -v197
	v_exp_f32_e32 v211, v84
	v_fma_f32 v84, v90, s3, -v197
	v_exp_f32_e32 v212, v84
	ds_read_b64_tr_b16 v[84:85], v236 offset:8192
	ds_read_b64_tr_b16 v[86:87], v236 offset:10240
	v_cvt_pk_bf16_f32 v80, v80, v81
	v_cvt_pk_bf16_f32 v81, v82, v83
	v_cvt_pk_bf16_f32 v82, v199, v198
	v_cvt_pk_bf16_f32 v83, v200, v201
	ds_read_b64_tr_b16 v[198:199], v237 offset:8192
	ds_read_b64_tr_b16 v[200:201], v237 offset:10240
	ds_read_b64_tr_b16 v[202:203], v236 offset:12288
	ds_read_b64_tr_b16 v[204:205], v236 offset:14336
	s_waitcnt lgkmcnt(4)
	v_mfma_f32_32x32x16_bf16 v[48:63], v[84:87], v[80:83], v[48:63]
	v_add_f32_e32 v84, v211, v88
	v_add_f32_e32 v215, v212, v84
	ds_read_b64_tr_b16 v[84:85], v238 offset:8192
	ds_read_b64_tr_b16 v[86:87], v238 offset:10240
	ds_read_b64_tr_b16 v[206:207], v237 offset:12288
	ds_read_b64_tr_b16 v[208:209], v237 offset:14336
	v_fma_f32 v88, v91, s3, -v197
	v_exp_f32_e32 v217, v88
	s_waitcnt lgkmcnt(6)
	v_mfma_f32_32x32x16_bf16 v[32:47], v[198:201], v[80:83], v[32:47]
	ds_read_b64_tr_b16 v[88:89], v239 offset:8192
	ds_read_b64_tr_b16 v[90:91], v239 offset:10240
	ds_read_b64_tr_b16 v[198:199], v238 offset:12288
	ds_read_b64_tr_b16 v[200:201], v238 offset:14336
	v_fma_f32 v94, v94, s3, -v197
	v_exp_f32_e32 v94, v94
	v_fma_f32 v64, v64, s3, -v197
	v_fma_f32 v78, v78, s3, -v197
	s_waitcnt lgkmcnt(6)
	v_mfma_f32_32x32x16_bf16 v[16:31], v[84:87], v[80:83], v[16:31]
	v_fma_f32 v84, v92, s3, -v197
	v_exp_f32_e32 v92, v84
	v_fma_f32 v84, v93, s3, -v197
	v_exp_f32_e32 v93, v84
	ds_read_b64_tr_b16 v[84:85], v239 offset:12288
	ds_read_b64_tr_b16 v[86:87], v239 offset:14336
	s_waitcnt lgkmcnt(4)
	v_mfma_f32_32x32x16_bf16 v[0:15], v[88:91], v[80:83], v[0:15]
	v_fma_f32 v80, v95, s3, -v197
	v_exp_f32_e32 v95, v80
	v_cvt_pk_bf16_f32 v80, v210, v211
	v_cvt_pk_bf16_f32 v81, v212, v217
	v_cvt_pk_bf16_f32 v82, v92, v93
	v_cvt_pk_bf16_f32 v83, v94, v95
	s_nop 1
	v_mfma_f32_32x32x16_bf16 v[48:63], v[202:205], v[80:83], v[48:63]
	v_exp_f32_e32 v202, v64
	v_fma_f32 v64, v65, s3, -v197
	v_exp_f32_e32 v203, v64
	v_fma_f32 v64, v66, s3, -v197
	v_exp_f32_e32 v204, v64
	v_fma_f32 v64, v67, s3, -v197
	v_exp_f32_e32 v205, v64
	v_fma_f32 v64, v68, s3, -v197
	v_mfma_f32_32x32x16_bf16 v[32:47], v[206:209], v[80:83], v[32:47]
	v_exp_f32_e32 v206, v64
	v_fma_f32 v64, v69, s3, -v197
	v_exp_f32_e32 v207, v64
	v_fma_f32 v64, v70, s3, -v197
	v_exp_f32_e32 v208, v64
	v_fma_f32 v64, v71, s3, -v197
	ds_read_b64_tr_b16 v[68:69], v236 offset:16384
	ds_read_b64_tr_b16 v[70:71], v236 offset:18432
	s_waitcnt lgkmcnt(4)
	v_mfma_f32_32x32x16_bf16 v[16:31], v[198:201], v[80:83], v[16:31]
	v_exp_f32_e32 v198, v64
	v_fma_f32 v64, v72, s3, -v197
	v_exp_f32_e32 v199, v64
	v_cvt_pk_bf16_f32 v64, v202, v203
	v_cvt_pk_bf16_f32 v65, v204, v205
	v_cvt_pk_bf16_f32 v66, v206, v207
	v_cvt_pk_bf16_f32 v67, v208, v198
	s_waitcnt lgkmcnt(2)
	v_mfma_f32_32x32x16_bf16 v[0:15], v[84:87], v[80:83], v[0:15]
	ds_read_b64_tr_b16 v[80:81], v237 offset:16384
	ds_read_b64_tr_b16 v[82:83], v237 offset:18432
	ds_read_b64_tr_b16 v[84:85], v236 offset:20480
	ds_read_b64_tr_b16 v[86:87], v236 offset:22528
	v_fma_f32 v72, v74, s3, -v197
	v_exp_f32_e32 v201, v72
	v_fma_f32 v72, v75, s3, -v197
	v_exp_f32_e32 v209, v72
	s_waitcnt lgkmcnt(4)
	v_mfma_f32_32x32x16_bf16 v[48:63], v[68:71], v[64:67], v[48:63]
	v_fma_f32 v68, v73, s3, -v197
	v_exp_f32_e32 v200, v68
	ds_read_b64_tr_b16 v[68:69], v238 offset:16384
	ds_read_b64_tr_b16 v[70:71], v238 offset:18432
	ds_read_b64_tr_b16 v[88:89], v237 offset:20480
	ds_read_b64_tr_b16 v[90:91], v237 offset:22528
	s_waitcnt lgkmcnt(6)
	v_mfma_f32_32x32x16_bf16 v[32:47], v[80:83], v[64:67], v[32:47]
	ds_read_b64_tr_b16 v[72:73], v239 offset:16384
	ds_read_b64_tr_b16 v[74:75], v239 offset:18432
	ds_read_b64_tr_b16 v[80:81], v238 offset:20480
	ds_read_b64_tr_b16 v[82:83], v238 offset:22528
	s_waitcnt lgkmcnt(2)
	v_mfma_f32_32x32x16_bf16 v[0:15], v[72:75], v[64:67], v[0:15]
	v_add_f32_e32 v74, v217, v215
	v_add_f32_e32 v74, v92, v74
	v_add_f32_e32 v74, v93, v74
	v_add_f32_e32 v74, v94, v74
	v_add_f32_e32 v74, v95, v74
	v_add_f32_e32 v74, v202, v74
	v_add_f32_e32 v74, v203, v74
	v_mfma_f32_32x32x16_bf16 v[16:31], v[68:71], v[64:67], v[16:31]
	v_fma_f32 v68, v76, s3, -v197
	v_add_f32_e32 v74, v204, v74
	v_exp_f32_e32 v76, v68
	v_fma_f32 v68, v77, s3, -v197
	v_fma_f32 v64, v79, s3, -v197
	v_add_f32_e32 v74, v205, v74
	v_exp_f32_e32 v77, v68
	ds_read_b64_tr_b16 v[68:69], v239 offset:20480
	ds_read_b64_tr_b16 v[70:71], v239 offset:22528
	v_exp_f32_e32 v72, v78
	v_exp_f32_e32 v73, v64
	v_add_f32_e32 v74, v206, v74
	v_add_f32_e32 v74, v207, v74
	v_add_f32_e32 v74, v208, v74
	v_add_f32_e32 v74, v198, v74
	v_cvt_pk_bf16_f32 v64, v199, v200
	v_cvt_pk_bf16_f32 v65, v201, v209
	v_cvt_pk_bf16_f32 v66, v76, v77
	v_cvt_pk_bf16_f32 v67, v72, v73
	v_add_f32_e32 v74, v199, v74
	v_add_f32_e32 v74, v200, v74
	v_mfma_f32_32x32x16_bf16 v[48:63], v[84:87], v[64:67], v[48:63]
	v_add_f32_e32 v74, v201, v74
	v_add_f32_e32 v74, v209, v74
	v_add_f32_e32 v74, v76, v74
	v_add_f32_e32 v74, v77, v74
	v_add_f32_e32 v72, v72, v74
	v_add_f32_e32 v72, v73, v72
	v_add_f32_e32 v196, v196, v72
	v_mfma_f32_32x32x16_bf16 v[32:47], v[88:91], v[64:67], v[32:47]
	s_waitcnt lgkmcnt(2)
	v_mfma_f32_32x32x16_bf16 v[16:31], v[80:83], v[64:67], v[16:31]
	s_waitcnt lgkmcnt(0)
	v_mfma_f32_32x32x16_bf16 v[0:15], v[68:71], v[64:67], v[0:15]

.LBB0_192:
	v_cmp_lt_u32_e32 vcc, s8, v119
	s_and_saveexec_b64 s[18:19], vcc
	s_cbranch_execz .LBB0_183
	ds_read_b128 v[220:223], v189 offset:24576
	ds_read_b128 v[68:71], v189 offset:28672
	ds_read_b128 v[224:227], v190 offset:24576
	ds_read_b128 v[142:145], v190 offset:28672
	ds_read_b128 v[228:231], v191 offset:24576
	ds_read_b128 v[146:149], v191 offset:28672
	ds_read_b128 v[232:235], v192 offset:24576
	ds_read_b128 v[150:153], v192 offset:28672
	s_waitcnt lgkmcnt(7)
	v_mfma_f32_32x32x16_bf16 v[80:95], v[220:223], v[96:99], 0
	s_waitcnt lgkmcnt(5)
	v_mfma_f32_32x32x16_bf16 v[80:95], v[224:227], v[100:103], v[80:95]
	s_waitcnt lgkmcnt(3)
	v_mfma_f32_32x32x16_bf16 v[80:95], v[228:231], v[104:107], v[80:95]
	s_waitcnt lgkmcnt(1)
	v_mfma_f32_32x32x16_bf16 v[80:95], v[232:235], v[108:111], v[80:95]
	s_waitcnt lgkmcnt(0)
	v_mfma_f32_32x32x16_bf16 v[64:79], v[68:71], v[96:99], 0
	v_mfma_f32_32x32x16_bf16 v[64:79], v[142:145], v[100:103], v[64:79]
	s_nop 9
	v_max_f32_e32 v142, v80, v81
	v_max3_f32 v142, v142, v82, v83
	v_max3_f32 v142, v142, v84, v85
	v_max3_f32 v142, v142, v86, v87
	v_max3_f32 v142, v142, v88, v89
	v_mfma_f32_32x32x16_bf16 v[64:79], v[146:149], v[104:107], v[64:79]
	v_max3_f32 v142, v142, v90, v91
	v_max3_f32 v142, v142, v92, v93
	v_max3_f32 v142, v142, v94, v95
	v_mfma_f32_32x32x16_bf16 v[64:79], v[150:153], v[108:111], v[64:79]
	s_nop 11
	v_max3_f32 v142, v142, v64, v65
	v_max3_f32 v142, v142, v66, v67
	v_max3_f32 v142, v142, v68, v69
	v_max3_f32 v142, v142, v70, v71
	v_max3_f32 v142, v142, v72, v73
	v_max3_f32 v142, v142, v74, v75
	v_max3_f32 v142, v142, v76, v77
	v_max3_f32 v142, v142, v78, v79
	v_mov_b32_e32 v143, v142
	s_nop 1
	v_permlane32_swap_b32_e32 v142, v143
	v_max_f32_e32 v142, v142, v143
	v_mul_f32_e32 v142, 0x3e38aa3b, v142
	v_add_f32_e32 v143, 0x41000000, v197
	v_cmp_gt_f32_e32 vcc, v142, v143
	s_cbranch_vccz .LBB0_182
	s_nop 0
	v_cndmask_b32_e32 v143, v197, v142, vcc
	v_sub_f32_e32 v142, v197, v143
	v_exp_f32_e32 v142, v142
	v_mov_b32_e32 v197, v143
	v_pk_mul_f32 v[62:63], v[62:63], v[142:143] op_sel_hi:[1,0]
	v_pk_mul_f32 v[60:61], v[60:61], v[142:143] op_sel_hi:[1,0]
	v_pk_mul_f32 v[58:59], v[58:59], v[142:143] op_sel_hi:[1,0]
	v_pk_mul_f32 v[56:57], v[56:57], v[142:143] op_sel_hi:[1,0]
	v_pk_mul_f32 v[54:55], v[54:55], v[142:143] op_sel_hi:[1,0]
	v_pk_mul_f32 v[52:53], v[52:53], v[142:143] op_sel_hi:[1,0]
	v_pk_mul_f32 v[50:51], v[50:51], v[142:143] op_sel_hi:[1,0]
	v_pk_mul_f32 v[48:49], v[48:49], v[142:143] op_sel_hi:[1,0]
	v_pk_mul_f32 v[46:47], v[46:47], v[142:143] op_sel_hi:[1,0]
	v_pk_mul_f32 v[44:45], v[44:45], v[142:143] op_sel_hi:[1,0]
	v_pk_mul_f32 v[42:43], v[42:43], v[142:143] op_sel_hi:[1,0]
	v_pk_mul_f32 v[40:41], v[40:41], v[142:143] op_sel_hi:[1,0]
	v_pk_mul_f32 v[38:39], v[38:39], v[142:143] op_sel_hi:[1,0]
	v_pk_mul_f32 v[36:37], v[36:37], v[142:143] op_sel_hi:[1,0]
	v_pk_mul_f32 v[34:35], v[34:35], v[142:143] op_sel_hi:[1,0]
	v_pk_mul_f32 v[32:33], v[32:33], v[142:143] op_sel_hi:[1,0]
	v_pk_mul_f32 v[30:31], v[30:31], v[142:143] op_sel_hi:[1,0]
	v_pk_mul_f32 v[28:29], v[28:29], v[142:143] op_sel_hi:[1,0]
	v_pk_mul_f32 v[26:27], v[26:27], v[142:143] op_sel_hi:[1,0]
	v_pk_mul_f32 v[24:25], v[24:25], v[142:143] op_sel_hi:[1,0]
	v_pk_mul_f32 v[22:23], v[22:23], v[142:143] op_sel_hi:[1,0]
	v_pk_mul_f32 v[20:21], v[20:21], v[142:143] op_sel_hi:[1,0]
	v_pk_mul_f32 v[18:19], v[18:19], v[142:143] op_sel_hi:[1,0]
	v_pk_mul_f32 v[16:17], v[16:17], v[142:143] op_sel_hi:[1,0]
	v_pk_mul_f32 v[14:15], v[14:15], v[142:143] op_sel_hi:[1,0]
	v_pk_mul_f32 v[12:13], v[12:13], v[142:143] op_sel_hi:[1,0]
	v_pk_mul_f32 v[10:11], v[10:11], v[142:143] op_sel_hi:[1,0]
	v_pk_mul_f32 v[8:9], v[8:9], v[142:143] op_sel_hi:[1,0]
	v_pk_mul_f32 v[6:7], v[6:7], v[142:143] op_sel_hi:[1,0]
	v_pk_mul_f32 v[4:5], v[4:5], v[142:143] op_sel_hi:[1,0]
	v_pk_mul_f32 v[2:3], v[2:3], v[142:143] op_sel_hi:[1,0]
	v_pk_mul_f32 v[0:1], v[0:1], v[142:143] op_sel_hi:[1,0]
	v_mul_f32_e32 v196, v196, v142
	s_branch .LBB0_182

.LBB0_196:
	v_fma_f32 v80, v80, s3, -v145
	v_exp_f32_e32 v80, v80
	v_fma_f32 v81, v81, s3, -v145
	v_fma_f32 v82, v82, s3, -v145
	v_exp_f32_e32 v81, v81
	v_exp_f32_e32 v82, v82
	v_fma_f32 v83, v83, s3, -v145
	v_exp_f32_e32 v83, v83
	v_fma_f32 v84, v84, s3, -v145
	v_exp_f32_e32 v133, v84
	v_fma_f32 v85, v85, s3, -v145
	v_add_f32_e32 v84, v81, v80
	v_exp_f32_e32 v132, v85
	v_fma_f32 v85, v86, s3, -v145
	v_add_f32_e32 v84, v82, v84
	v_exp_f32_e32 v134, v85
	v_fma_f32 v85, v87, s3, -v145
	v_add_f32_e32 v84, v83, v84
	v_exp_f32_e32 v135, v85
	v_fma_f32 v85, v88, s3, -v145
	v_add_f32_e32 v84, v133, v84
	v_exp_f32_e32 v146, v85
	v_add_f32_e32 v84, v132, v84
	v_add_f32_e32 v84, v134, v84
	v_add_f32_e32 v84, v135, v84
	v_add_f32_e32 v88, v146, v84
	v_fma_f32 v84, v89, s3, -v145
	v_exp_f32_e32 v147, v84
	v_fma_f32 v84, v90, s3, -v145
	v_exp_f32_e32 v148, v84
	ds_read_b64_tr_b16 v[84:85], v236 offset:32768
	ds_read_b64_tr_b16 v[86:87], v236 offset:34816
	v_cvt_pk_bf16_f32 v80, v80, v81
	v_cvt_pk_bf16_f32 v81, v82, v83
	v_cvt_pk_bf16_f32 v82, v133, v132
	v_cvt_pk_bf16_f32 v83, v134, v135
	ds_read_b64_tr_b16 v[132:133], v237 offset:32768
	ds_read_b64_tr_b16 v[134:135], v237 offset:34816
	ds_read_b64_tr_b16 v[136:137], v236 offset:36864
	ds_read_b64_tr_b16 v[138:139], v236 offset:38912
	s_waitcnt lgkmcnt(4)
	v_mfma_f32_32x32x16_bf16 v[48:63], v[84:87], v[80:83], v[48:63]
	v_add_f32_e32 v84, v147, v88
	v_add_f32_e32 v151, v148, v84
	ds_read_b64_tr_b16 v[84:85], v238 offset:32768
	ds_read_b64_tr_b16 v[86:87], v238 offset:34816
	ds_read_b64_tr_b16 v[140:141], v237 offset:36864
	ds_read_b64_tr_b16 v[142:143], v237 offset:38912
	v_fma_f32 v88, v91, s3, -v145
	v_exp_f32_e32 v153, v88
	s_waitcnt lgkmcnt(6)
	v_mfma_f32_32x32x16_bf16 v[32:47], v[132:135], v[80:83], v[32:47]
	ds_read_b64_tr_b16 v[88:89], v239 offset:32768
	ds_read_b64_tr_b16 v[90:91], v239 offset:34816
	ds_read_b64_tr_b16 v[132:133], v238 offset:36864
	ds_read_b64_tr_b16 v[134:135], v238 offset:38912
	v_fma_f32 v94, v94, s3, -v145
	v_exp_f32_e32 v94, v94
	v_fma_f32 v64, v64, s3, -v145
	v_fma_f32 v78, v78, s3, -v145
	s_waitcnt lgkmcnt(6)
	v_mfma_f32_32x32x16_bf16 v[16:31], v[84:87], v[80:83], v[16:31]
	v_fma_f32 v84, v92, s3, -v145
	v_exp_f32_e32 v92, v84
	v_fma_f32 v84, v93, s3, -v145
	v_exp_f32_e32 v93, v84
	ds_read_b64_tr_b16 v[84:85], v239 offset:36864
	ds_read_b64_tr_b16 v[86:87], v239 offset:38912
	s_waitcnt lgkmcnt(4)
	v_mfma_f32_32x32x16_bf16 v[0:15], v[88:91], v[80:83], v[0:15]
	v_fma_f32 v80, v95, s3, -v145
	v_exp_f32_e32 v95, v80
	v_cvt_pk_bf16_f32 v80, v146, v147
	v_cvt_pk_bf16_f32 v81, v148, v153
	v_cvt_pk_bf16_f32 v82, v92, v93
	v_cvt_pk_bf16_f32 v83, v94, v95
	s_nop 1
	v_mfma_f32_32x32x16_bf16 v[48:63], v[136:139], v[80:83], v[48:63]
	v_exp_f32_e32 v136, v64
	v_fma_f32 v64, v65, s3, -v145
	v_exp_f32_e32 v137, v64
	v_fma_f32 v64, v66, s3, -v145
	v_exp_f32_e32 v138, v64
	v_fma_f32 v64, v67, s3, -v145
	v_exp_f32_e32 v139, v64
	v_fma_f32 v64, v68, s3, -v145
	v_mfma_f32_32x32x16_bf16 v[32:47], v[140:143], v[80:83], v[32:47]
	v_exp_f32_e32 v140, v64
	v_fma_f32 v64, v69, s3, -v145
	v_exp_f32_e32 v141, v64
	v_fma_f32 v64, v70, s3, -v145
	v_exp_f32_e32 v142, v64
	v_fma_f32 v64, v71, s3, -v145
	ds_read_b64_tr_b16 v[68:69], v236 offset:40960
	ds_read_b64_tr_b16 v[70:71], v236 offset:43008
	s_waitcnt lgkmcnt(4)
	v_mfma_f32_32x32x16_bf16 v[16:31], v[132:135], v[80:83], v[16:31]
	v_exp_f32_e32 v132, v64
	v_fma_f32 v64, v72, s3, -v145
	v_exp_f32_e32 v133, v64
	v_cvt_pk_bf16_f32 v64, v136, v137
	v_cvt_pk_bf16_f32 v65, v138, v139
	v_cvt_pk_bf16_f32 v66, v140, v141
	v_cvt_pk_bf16_f32 v67, v142, v132
	s_waitcnt lgkmcnt(2)
	v_mfma_f32_32x32x16_bf16 v[0:15], v[84:87], v[80:83], v[0:15]
	ds_read_b64_tr_b16 v[80:81], v237 offset:40960
	ds_read_b64_tr_b16 v[82:83], v237 offset:43008
	ds_read_b64_tr_b16 v[84:85], v236 offset:45056
	ds_read_b64_tr_b16 v[86:87], v236 offset:47104
	v_fma_f32 v72, v74, s3, -v145
	v_exp_f32_e32 v135, v72
	v_fma_f32 v72, v75, s3, -v145
	v_exp_f32_e32 v143, v72
	s_waitcnt lgkmcnt(4)
	v_mfma_f32_32x32x16_bf16 v[48:63], v[68:71], v[64:67], v[48:63]
	v_fma_f32 v68, v73, s3, -v145
	v_exp_f32_e32 v134, v68
	ds_read_b64_tr_b16 v[68:69], v238 offset:40960
	ds_read_b64_tr_b16 v[70:71], v238 offset:43008
	ds_read_b64_tr_b16 v[88:89], v237 offset:45056
	ds_read_b64_tr_b16 v[90:91], v237 offset:47104
	s_waitcnt lgkmcnt(6)
	v_mfma_f32_32x32x16_bf16 v[32:47], v[80:83], v[64:67], v[32:47]
	ds_read_b64_tr_b16 v[72:73], v239 offset:40960
	ds_read_b64_tr_b16 v[74:75], v239 offset:43008
	ds_read_b64_tr_b16 v[80:81], v238 offset:45056
	ds_read_b64_tr_b16 v[82:83], v238 offset:47104
	s_waitcnt lgkmcnt(2)
	v_mfma_f32_32x32x16_bf16 v[0:15], v[72:75], v[64:67], v[0:15]
	v_add_f32_e32 v74, v153, v151
	v_add_f32_e32 v74, v92, v74
	v_add_f32_e32 v74, v93, v74
	v_add_f32_e32 v74, v94, v74
	v_add_f32_e32 v74, v95, v74
	v_add_f32_e32 v74, v136, v74
	v_add_f32_e32 v74, v137, v74
	v_mfma_f32_32x32x16_bf16 v[16:31], v[68:71], v[64:67], v[16:31]
	v_fma_f32 v68, v76, s3, -v145
	v_add_f32_e32 v74, v138, v74
	v_exp_f32_e32 v76, v68
	v_fma_f32 v68, v77, s3, -v145
	v_fma_f32 v64, v79, s3, -v145
	v_add_f32_e32 v74, v139, v74
	v_exp_f32_e32 v77, v68
	ds_read_b64_tr_b16 v[68:69], v239 offset:45056
	ds_read_b64_tr_b16 v[70:71], v239 offset:47104
	v_exp_f32_e32 v72, v78
	v_exp_f32_e32 v73, v64
	v_add_f32_e32 v74, v140, v74
	v_add_f32_e32 v74, v141, v74
	v_add_f32_e32 v74, v142, v74
	v_add_f32_e32 v74, v132, v74
	v_cvt_pk_bf16_f32 v64, v133, v134
	v_cvt_pk_bf16_f32 v65, v135, v143
	v_cvt_pk_bf16_f32 v66, v76, v77
	v_cvt_pk_bf16_f32 v67, v72, v73
	v_add_f32_e32 v74, v133, v74
	v_add_f32_e32 v74, v134, v74
	v_mfma_f32_32x32x16_bf16 v[48:63], v[84:87], v[64:67], v[48:63]
	v_add_f32_e32 v74, v135, v74
	v_add_f32_e32 v74, v143, v74
	v_add_f32_e32 v74, v76, v74
	v_add_f32_e32 v74, v77, v74
	v_add_f32_e32 v72, v72, v74
	v_add_f32_e32 v72, v73, v72
	v_add_f32_e32 v144, v144, v72
	v_mfma_f32_32x32x16_bf16 v[32:47], v[88:91], v[64:67], v[32:47]
	s_waitcnt lgkmcnt(2)
	v_mfma_f32_32x32x16_bf16 v[16:31], v[80:83], v[64:67], v[16:31]
	s_waitcnt lgkmcnt(0)
	v_mfma_f32_32x32x16_bf16 v[0:15], v[68:71], v[64:67], v[0:15]

.LBB0_200:
	v_cmp_le_u32_e32 vcc, s8, v119
	s_and_saveexec_b64 s[14:15], vcc
	s_cbranch_execz .LBB0_204
	ds_read_b128 v[220:223], v189
	ds_read_b128 v[68:71], v189 offset:4096
	ds_read_b128 v[224:227], v190
	ds_read_b128 v[146:149], v190 offset:4096
	ds_read_b128 v[228:231], v191
	ds_read_b128 v[150:153], v191 offset:4096
	ds_read_b128 v[232:235], v192
	ds_read_b128 v[194:197], v192 offset:4096
	s_waitcnt lgkmcnt(7)
	v_mfma_f32_32x32x16_bf16 v[80:95], v[220:223], v[96:99], 0
	s_waitcnt lgkmcnt(5)
	v_mfma_f32_32x32x16_bf16 v[80:95], v[224:227], v[100:103], v[80:95]
	s_waitcnt lgkmcnt(3)
	v_mfma_f32_32x32x16_bf16 v[80:95], v[228:231], v[104:107], v[80:95]
	s_waitcnt lgkmcnt(1)
	v_mfma_f32_32x32x16_bf16 v[80:95], v[232:235], v[108:111], v[80:95]
	s_waitcnt lgkmcnt(0)
	v_mfma_f32_32x32x16_bf16 v[64:79], v[68:71], v[96:99], 0
	v_mfma_f32_32x32x16_bf16 v[64:79], v[146:149], v[100:103], v[64:79]
	s_nop 9
	v_max_f32_e32 v146, v80, v81
	v_max3_f32 v146, v146, v82, v83
	v_max3_f32 v146, v146, v84, v85
	v_max3_f32 v146, v146, v86, v87
	v_max3_f32 v146, v146, v88, v89
	v_mfma_f32_32x32x16_bf16 v[64:79], v[150:153], v[104:107], v[64:79]
	v_max3_f32 v146, v146, v90, v91
	v_max3_f32 v146, v146, v92, v93
	v_max3_f32 v146, v146, v94, v95
	v_mfma_f32_32x32x16_bf16 v[64:79], v[194:197], v[108:111], v[64:79]
	s_nop 11
	v_max3_f32 v146, v146, v64, v65
	v_max3_f32 v146, v146, v66, v67
	v_max3_f32 v146, v146, v68, v69
	v_max3_f32 v146, v146, v70, v71
	v_max3_f32 v146, v146, v72, v73
	v_max3_f32 v146, v146, v74, v75
	v_max3_f32 v146, v146, v76, v77
	v_max3_f32 v146, v146, v78, v79
	v_mov_b32_e32 v147, v146
	s_nop 1
	v_permlane32_swap_b32_e32 v146, v147
	v_max_f32_e32 v146, v146, v147
	v_mul_f32_e32 v146, 0x3e38aa3b, v146
	v_add_f32_e32 v147, 0x41000000, v145
	v_cmp_gt_f32_e32 vcc, v146, v147
	s_cbranch_vccz .LBB0_203
	s_nop 0
	v_cndmask_b32_e32 v147, v145, v146, vcc
	v_sub_f32_e32 v145, v145, v147
	v_exp_f32_e32 v146, v145
	v_mov_b32_e32 v145, v147
	v_pk_mul_f32 v[62:63], v[62:63], v[146:147] op_sel_hi:[1,0]
	v_pk_mul_f32 v[60:61], v[60:61], v[146:147] op_sel_hi:[1,0]
	v_pk_mul_f32 v[58:59], v[58:59], v[146:147] op_sel_hi:[1,0]
	v_pk_mul_f32 v[56:57], v[56:57], v[146:147] op_sel_hi:[1,0]
	v_pk_mul_f32 v[54:55], v[54:55], v[146:147] op_sel_hi:[1,0]
	v_pk_mul_f32 v[52:53], v[52:53], v[146:147] op_sel_hi:[1,0]
	v_pk_mul_f32 v[50:51], v[50:51], v[146:147] op_sel_hi:[1,0]
	v_pk_mul_f32 v[48:49], v[48:49], v[146:147] op_sel_hi:[1,0]
	v_pk_mul_f32 v[46:47], v[46:47], v[146:147] op_sel_hi:[1,0]
	v_pk_mul_f32 v[44:45], v[44:45], v[146:147] op_sel_hi:[1,0]
	v_pk_mul_f32 v[42:43], v[42:43], v[146:147] op_sel_hi:[1,0]
	v_pk_mul_f32 v[40:41], v[40:41], v[146:147] op_sel_hi:[1,0]
	v_pk_mul_f32 v[38:39], v[38:39], v[146:147] op_sel_hi:[1,0]
	v_pk_mul_f32 v[36:37], v[36:37], v[146:147] op_sel_hi:[1,0]
	v_pk_mul_f32 v[34:35], v[34:35], v[146:147] op_sel_hi:[1,0]
	v_pk_mul_f32 v[32:33], v[32:33], v[146:147] op_sel_hi:[1,0]
	v_pk_mul_f32 v[30:31], v[30:31], v[146:147] op_sel_hi:[1,0]
	v_pk_mul_f32 v[28:29], v[28:29], v[146:147] op_sel_hi:[1,0]
	v_pk_mul_f32 v[26:27], v[26:27], v[146:147] op_sel_hi:[1,0]
	v_pk_mul_f32 v[24:25], v[24:25], v[146:147] op_sel_hi:[1,0]
	v_pk_mul_f32 v[22:23], v[22:23], v[146:147] op_sel_hi:[1,0]
	v_pk_mul_f32 v[20:21], v[20:21], v[146:147] op_sel_hi:[1,0]
	v_pk_mul_f32 v[18:19], v[18:19], v[146:147] op_sel_hi:[1,0]
	v_pk_mul_f32 v[16:17], v[16:17], v[146:147] op_sel_hi:[1,0]
	v_pk_mul_f32 v[14:15], v[14:15], v[146:147] op_sel_hi:[1,0]
	v_pk_mul_f32 v[12:13], v[12:13], v[146:147] op_sel_hi:[1,0]
	v_pk_mul_f32 v[10:11], v[10:11], v[146:147] op_sel_hi:[1,0]
	v_pk_mul_f32 v[8:9], v[8:9], v[146:147] op_sel_hi:[1,0]
	v_pk_mul_f32 v[6:7], v[6:7], v[146:147] op_sel_hi:[1,0]
	v_pk_mul_f32 v[4:5], v[4:5], v[146:147] op_sel_hi:[1,0]
	v_pk_mul_f32 v[2:3], v[2:3], v[146:147] op_sel_hi:[1,0]
	v_pk_mul_f32 v[0:1], v[0:1], v[146:147] op_sel_hi:[1,0]
	v_mul_f32_e32 v144, v144, v146
.LBB0_203:
	v_fma_f32 v80, v80, s3, -v145
	v_exp_f32_e32 v80, v80
	v_fma_f32 v81, v81, s3, -v145
	v_fma_f32 v82, v82, s3, -v145
	v_exp_f32_e32 v81, v81
	v_exp_f32_e32 v82, v82
	v_fma_f32 v83, v83, s3, -v145
	v_exp_f32_e32 v83, v83
	v_fma_f32 v84, v84, s3, -v145
	v_exp_f32_e32 v147, v84
	v_fma_f32 v85, v85, s3, -v145
	v_add_f32_e32 v84, v81, v80
	v_exp_f32_e32 v146, v85
	v_fma_f32 v85, v86, s3, -v145
	v_add_f32_e32 v84, v82, v84
	v_exp_f32_e32 v148, v85
	v_fma_f32 v85, v87, s3, -v145
	v_add_f32_e32 v84, v83, v84
	v_exp_f32_e32 v149, v85
	v_fma_f32 v85, v88, s3, -v145
	v_add_f32_e32 v84, v147, v84
	v_exp_f32_e32 v198, v85
	v_add_f32_e32 v84, v146, v84
	v_add_f32_e32 v84, v148, v84
	v_add_f32_e32 v84, v149, v84
	v_add_f32_e32 v88, v198, v84
	v_fma_f32 v84, v89, s3, -v145
	v_exp_f32_e32 v199, v84
	v_fma_f32 v84, v90, s3, -v145
	v_exp_f32_e32 v200, v84
	ds_read_b64_tr_b16 v[84:85], v236 offset:8192
	ds_read_b64_tr_b16 v[86:87], v236 offset:10240
	v_cvt_pk_bf16_f32 v80, v80, v81
	v_cvt_pk_bf16_f32 v81, v82, v83
	v_cvt_pk_bf16_f32 v82, v147, v146
	v_cvt_pk_bf16_f32 v83, v148, v149
	ds_read_b64_tr_b16 v[146:147], v237 offset:8192
	ds_read_b64_tr_b16 v[148:149], v237 offset:10240
	ds_read_b64_tr_b16 v[150:151], v236 offset:12288
	ds_read_b64_tr_b16 v[152:153], v236 offset:14336
	s_waitcnt lgkmcnt(4)
	v_mfma_f32_32x32x16_bf16 v[48:63], v[84:87], v[80:83], v[48:63]
	v_add_f32_e32 v84, v199, v88
	v_add_f32_e32 v203, v200, v84
	ds_read_b64_tr_b16 v[84:85], v238 offset:8192
	ds_read_b64_tr_b16 v[86:87], v238 offset:10240
	ds_read_b64_tr_b16 v[194:195], v237 offset:12288
	ds_read_b64_tr_b16 v[196:197], v237 offset:14336
	v_fma_f32 v88, v91, s3, -v145
	v_exp_f32_e32 v205, v88
	s_waitcnt lgkmcnt(6)
	v_mfma_f32_32x32x16_bf16 v[32:47], v[146:149], v[80:83], v[32:47]
	ds_read_b64_tr_b16 v[88:89], v239 offset:8192
	ds_read_b64_tr_b16 v[90:91], v239 offset:10240
	ds_read_b64_tr_b16 v[146:147], v238 offset:12288
	ds_read_b64_tr_b16 v[148:149], v238 offset:14336
	v_fma_f32 v94, v94, s3, -v145
	v_exp_f32_e32 v94, v94
	v_fma_f32 v64, v64, s3, -v145
	v_fma_f32 v78, v78, s3, -v145
	s_waitcnt lgkmcnt(6)
	v_mfma_f32_32x32x16_bf16 v[16:31], v[84:87], v[80:83], v[16:31]
	v_fma_f32 v84, v92, s3, -v145
	v_exp_f32_e32 v92, v84
	v_fma_f32 v84, v93, s3, -v145
	v_exp_f32_e32 v93, v84
	ds_read_b64_tr_b16 v[84:85], v239 offset:12288
	ds_read_b64_tr_b16 v[86:87], v239 offset:14336
	s_waitcnt lgkmcnt(4)
	v_mfma_f32_32x32x16_bf16 v[0:15], v[88:91], v[80:83], v[0:15]
	v_fma_f32 v80, v95, s3, -v145
	v_exp_f32_e32 v95, v80
	v_cvt_pk_bf16_f32 v80, v198, v199
	v_cvt_pk_bf16_f32 v81, v200, v205
	v_cvt_pk_bf16_f32 v82, v92, v93
	v_cvt_pk_bf16_f32 v83, v94, v95
	s_nop 1
	v_mfma_f32_32x32x16_bf16 v[48:63], v[150:153], v[80:83], v[48:63]
	v_exp_f32_e32 v150, v64
	v_fma_f32 v64, v65, s3, -v145
	v_exp_f32_e32 v151, v64
	v_fma_f32 v64, v66, s3, -v145
	v_exp_f32_e32 v152, v64
	v_fma_f32 v64, v67, s3, -v145
	v_exp_f32_e32 v153, v64
	v_fma_f32 v64, v68, s3, -v145
	v_mfma_f32_32x32x16_bf16 v[32:47], v[194:197], v[80:83], v[32:47]
	v_exp_f32_e32 v194, v64
	v_fma_f32 v64, v69, s3, -v145
	v_exp_f32_e32 v195, v64
	v_fma_f32 v64, v70, s3, -v145
	v_exp_f32_e32 v196, v64
	v_fma_f32 v64, v71, s3, -v145
	ds_read_b64_tr_b16 v[68:69], v236 offset:16384
	ds_read_b64_tr_b16 v[70:71], v236 offset:18432
	s_waitcnt lgkmcnt(4)
	v_mfma_f32_32x32x16_bf16 v[16:31], v[146:149], v[80:83], v[16:31]
	v_exp_f32_e32 v146, v64
	v_fma_f32 v64, v72, s3, -v145
	v_exp_f32_e32 v147, v64
	v_cvt_pk_bf16_f32 v64, v150, v151
	v_cvt_pk_bf16_f32 v65, v152, v153
	v_cvt_pk_bf16_f32 v66, v194, v195
	v_cvt_pk_bf16_f32 v67, v196, v146
	s_waitcnt lgkmcnt(2)
	v_mfma_f32_32x32x16_bf16 v[0:15], v[84:87], v[80:83], v[0:15]
	ds_read_b64_tr_b16 v[80:81], v237 offset:16384
	ds_read_b64_tr_b16 v[82:83], v237 offset:18432
	ds_read_b64_tr_b16 v[84:85], v236 offset:20480
	ds_read_b64_tr_b16 v[86:87], v236 offset:22528
	v_fma_f32 v72, v74, s3, -v145
	v_exp_f32_e32 v149, v72
	v_fma_f32 v72, v75, s3, -v145
	v_exp_f32_e32 v197, v72
	s_waitcnt lgkmcnt(4)
	v_mfma_f32_32x32x16_bf16 v[48:63], v[68:71], v[64:67], v[48:63]
	v_fma_f32 v68, v73, s3, -v145
	v_exp_f32_e32 v148, v68
	ds_read_b64_tr_b16 v[68:69], v238 offset:16384
	ds_read_b64_tr_b16 v[70:71], v238 offset:18432
	ds_read_b64_tr_b16 v[88:89], v237 offset:20480
	ds_read_b64_tr_b16 v[90:91], v237 offset:22528
	s_waitcnt lgkmcnt(6)
	v_mfma_f32_32x32x16_bf16 v[32:47], v[80:83], v[64:67], v[32:47]
	ds_read_b64_tr_b16 v[72:73], v239 offset:16384
	ds_read_b64_tr_b16 v[74:75], v239 offset:18432
	ds_read_b64_tr_b16 v[80:81], v238 offset:20480
	ds_read_b64_tr_b16 v[82:83], v238 offset:22528
	s_waitcnt lgkmcnt(2)
	v_mfma_f32_32x32x16_bf16 v[0:15], v[72:75], v[64:67], v[0:15]
	v_add_f32_e32 v74, v205, v203
	v_add_f32_e32 v74, v92, v74
	v_add_f32_e32 v74, v93, v74
	v_add_f32_e32 v74, v94, v74
	v_add_f32_e32 v74, v95, v74
	v_add_f32_e32 v74, v150, v74
	v_add_f32_e32 v74, v151, v74
	v_mfma_f32_32x32x16_bf16 v[16:31], v[68:71], v[64:67], v[16:31]
	v_fma_f32 v68, v76, s3, -v145
	v_add_f32_e32 v74, v152, v74
	v_exp_f32_e32 v76, v68
	v_fma_f32 v68, v77, s3, -v145
	v_fma_f32 v64, v79, s3, -v145
	v_add_f32_e32 v74, v153, v74
	v_exp_f32_e32 v77, v68
	ds_read_b64_tr_b16 v[68:69], v239 offset:20480
	ds_read_b64_tr_b16 v[70:71], v239 offset:22528
	v_exp_f32_e32 v72, v78
	v_exp_f32_e32 v73, v64
	v_add_f32_e32 v74, v194, v74
	v_add_f32_e32 v74, v195, v74
	v_add_f32_e32 v74, v196, v74
	v_add_f32_e32 v74, v146, v74
	v_cvt_pk_bf16_f32 v64, v147, v148
	v_cvt_pk_bf16_f32 v65, v149, v197
	v_cvt_pk_bf16_f32 v66, v76, v77
	v_cvt_pk_bf16_f32 v67, v72, v73
	v_add_f32_e32 v74, v147, v74
	v_add_f32_e32 v74, v148, v74
	v_mfma_f32_32x32x16_bf16 v[48:63], v[84:87], v[64:67], v[48:63]
	v_add_f32_e32 v74, v149, v74
	v_add_f32_e32 v74, v197, v74
	v_add_f32_e32 v74, v76, v74
	v_add_f32_e32 v74, v77, v74
	v_add_f32_e32 v72, v72, v74
	v_add_f32_e32 v72, v73, v72
	v_add_f32_e32 v144, v144, v72
	v_mfma_f32_32x32x16_bf16 v[32:47], v[88:91], v[64:67], v[32:47]
	s_waitcnt lgkmcnt(2)
	v_mfma_f32_32x32x16_bf16 v[16:31], v[80:83], v[64:67], v[16:31]
	s_waitcnt lgkmcnt(0)
	v_mfma_f32_32x32x16_bf16 v[0:15], v[68:71], v[64:67], v[0:15]

.LBB0_206:
	v_cmp_lt_u32_e32 vcc, s8, v119
	s_and_saveexec_b64 s[14:15], vcc
	s_cbranch_execz .LBB0_197
	ds_read_b128 v[220:223], v189 offset:24576
	ds_read_b128 v[68:71], v189 offset:28672
	ds_read_b128 v[224:227], v190 offset:24576
	ds_read_b128 v[132:135], v190 offset:28672
	ds_read_b128 v[228:231], v191 offset:24576
	ds_read_b128 v[136:139], v191 offset:28672
	ds_read_b128 v[232:235], v192 offset:24576
	ds_read_b128 v[140:143], v192 offset:28672
	s_waitcnt lgkmcnt(7)
	v_mfma_f32_32x32x16_bf16 v[80:95], v[220:223], v[96:99], 0
	s_waitcnt lgkmcnt(5)
	v_mfma_f32_32x32x16_bf16 v[80:95], v[224:227], v[100:103], v[80:95]
	s_waitcnt lgkmcnt(3)
	v_mfma_f32_32x32x16_bf16 v[80:95], v[228:231], v[104:107], v[80:95]
	s_waitcnt lgkmcnt(1)
	v_mfma_f32_32x32x16_bf16 v[80:95], v[232:235], v[108:111], v[80:95]
	s_waitcnt lgkmcnt(0)
	v_mfma_f32_32x32x16_bf16 v[64:79], v[68:71], v[96:99], 0
	v_mfma_f32_32x32x16_bf16 v[64:79], v[132:135], v[100:103], v[64:79]
	s_nop 9
	v_max_f32_e32 v132, v80, v81
	v_max3_f32 v132, v132, v82, v83
	v_max3_f32 v132, v132, v84, v85
	v_max3_f32 v132, v132, v86, v87
	v_max3_f32 v132, v132, v88, v89
	v_mfma_f32_32x32x16_bf16 v[64:79], v[136:139], v[104:107], v[64:79]
	v_max3_f32 v132, v132, v90, v91
	v_max3_f32 v132, v132, v92, v93
	v_max3_f32 v132, v132, v94, v95
	v_mfma_f32_32x32x16_bf16 v[64:79], v[140:143], v[108:111], v[64:79]
	s_nop 11
	v_max3_f32 v132, v132, v64, v65
	v_max3_f32 v132, v132, v66, v67
	v_max3_f32 v132, v132, v68, v69
	v_max3_f32 v132, v132, v70, v71
	v_max3_f32 v132, v132, v72, v73
	v_max3_f32 v132, v132, v74, v75
	v_max3_f32 v132, v132, v76, v77
	v_max3_f32 v132, v132, v78, v79
	v_mov_b32_e32 v133, v132
	s_nop 1
	v_permlane32_swap_b32_e32 v132, v133
	v_max_f32_e32 v132, v132, v133
	v_mul_f32_e32 v132, 0x3e38aa3b, v132
	v_add_f32_e32 v133, 0x41000000, v145
	v_cmp_gt_f32_e32 vcc, v132, v133
	s_cbranch_vccz .LBB0_196
	s_nop 0
	v_cndmask_b32_e32 v133, v145, v132, vcc
	v_sub_f32_e32 v132, v145, v133
	v_exp_f32_e32 v132, v132
	v_mov_b32_e32 v145, v133
	v_pk_mul_f32 v[62:63], v[62:63], v[132:133] op_sel_hi:[1,0]
	v_pk_mul_f32 v[60:61], v[60:61], v[132:133] op_sel_hi:[1,0]
	v_pk_mul_f32 v[58:59], v[58:59], v[132:133] op_sel_hi:[1,0]
	v_pk_mul_f32 v[56:57], v[56:57], v[132:133] op_sel_hi:[1,0]
	v_pk_mul_f32 v[54:55], v[54:55], v[132:133] op_sel_hi:[1,0]
	v_pk_mul_f32 v[52:53], v[52:53], v[132:133] op_sel_hi:[1,0]
	v_pk_mul_f32 v[50:51], v[50:51], v[132:133] op_sel_hi:[1,0]
	v_pk_mul_f32 v[48:49], v[48:49], v[132:133] op_sel_hi:[1,0]
	v_pk_mul_f32 v[46:47], v[46:47], v[132:133] op_sel_hi:[1,0]
	v_pk_mul_f32 v[44:45], v[44:45], v[132:133] op_sel_hi:[1,0]
	v_pk_mul_f32 v[42:43], v[42:43], v[132:133] op_sel_hi:[1,0]
	v_pk_mul_f32 v[40:41], v[40:41], v[132:133] op_sel_hi:[1,0]
	v_pk_mul_f32 v[38:39], v[38:39], v[132:133] op_sel_hi:[1,0]
	v_pk_mul_f32 v[36:37], v[36:37], v[132:133] op_sel_hi:[1,0]
	v_pk_mul_f32 v[34:35], v[34:35], v[132:133] op_sel_hi:[1,0]
	v_pk_mul_f32 v[32:33], v[32:33], v[132:133] op_sel_hi:[1,0]
	v_pk_mul_f32 v[30:31], v[30:31], v[132:133] op_sel_hi:[1,0]
	v_pk_mul_f32 v[28:29], v[28:29], v[132:133] op_sel_hi:[1,0]
	v_pk_mul_f32 v[26:27], v[26:27], v[132:133] op_sel_hi:[1,0]
	v_pk_mul_f32 v[24:25], v[24:25], v[132:133] op_sel_hi:[1,0]
	v_pk_mul_f32 v[22:23], v[22:23], v[132:133] op_sel_hi:[1,0]
	v_pk_mul_f32 v[20:21], v[20:21], v[132:133] op_sel_hi:[1,0]
	v_pk_mul_f32 v[18:19], v[18:19], v[132:133] op_sel_hi:[1,0]
	v_pk_mul_f32 v[16:17], v[16:17], v[132:133] op_sel_hi:[1,0]
	v_pk_mul_f32 v[14:15], v[14:15], v[132:133] op_sel_hi:[1,0]
	v_pk_mul_f32 v[12:13], v[12:13], v[132:133] op_sel_hi:[1,0]
	v_pk_mul_f32 v[10:11], v[10:11], v[132:133] op_sel_hi:[1,0]
	v_pk_mul_f32 v[8:9], v[8:9], v[132:133] op_sel_hi:[1,0]
	v_pk_mul_f32 v[6:7], v[6:7], v[132:133] op_sel_hi:[1,0]
	v_pk_mul_f32 v[4:5], v[4:5], v[132:133] op_sel_hi:[1,0]
	v_pk_mul_f32 v[2:3], v[2:3], v[132:133] op_sel_hi:[1,0]
	v_pk_mul_f32 v[0:1], v[0:1], v[132:133] op_sel_hi:[1,0]
	v_mul_f32_e32 v144, v144, v132
	s_branch .LBB0_196
